# gla_prep loads de-serialised (V/Q loads issued up front, single wait)
# speedup vs baseline: 1.0579x; 1.0030x over previous
; __device__ __forceinline__ float bf2f(unsigned short h) { return __uint_as_float((unsigned)h << 16); }
; __device__ __forceinline__ unsigned f2bfhw(float f) { return (unsigned)__builtin_bit_cast(unsigned short, (__bf16)f); }
; __device__ __forceinline__ f32x4 ld_bf4(const bf16_t* p) { u32x2 w = *(const u32x2*)p; return (f32x4){__uint_as_float(w.x << 16), __uint_as_float(w.x & 0xffff0000u), __uint_as_float(w.y << 16), __uint_as_float(w.y & 0xffff0000u)}; }
; #define LBAR() do { asm volatile("s_waitcnt lgkmcnt(0)" ::: "memory"); __builtin_amdgcn_s_barrier(); asm volatile("" ::: "memory"); } while (0)
; __device__ __forceinline__ void gla_prep(LAS unsigned char* lds, int ufirst, int ucount, const bf16_t* Qb, const bf16_t* Kb, const bf16_t* Vb, const bf16_t* LR, ...
;     ...
;         LBAR();
;         if (lat || dir == 0) {
; #pragma unroll
;             for (int j = 0; j < 4; ++j) { const int idx = tid + 512 * j, sp = idx & 63, c8 = (idx >> 6) * 8; const bf16x8 v = *(const bf16x8*)(Vb + (size_t)(row0 + sp) * VW + h * DV + c8);
; #pragma unroll
;                 for (int e = 0; e < 8; ++e) vT[(c8 + e) * 72 + sp] = (bf16_t)v[e]; }
;         }
;         bf16x8 afr[4], bfr;
; #pragma unroll
;         for (int pt = 0; pt < 4; ++pt) afr[pt] = *(const bf16x8*)(LR + (size_t)(row0 + 16 * pt + fr) * 256 + dir * 16 + (fq & 1) * 8);
;         { const float* wp = wsrc + (size_t)((fq & 1) * 8) * QKW + h * DK + 16 * wave + fr;
; #pragma unroll
;           for (int e = 0; e < 8; ++e) { const float wv = wp[e * QKW]; const unsigned hi = f2bfhw(wv); const float res = wv - bf2f((unsigned short)hi); bfr[e] = (short)(fq < 2 ? hi : f2bfhw(res)); } }
;         const f32x4 bias4 = *(const f32x4*)(bsrc + h * DK + 16 * wave + 4 * fq);
;         f32x4 k4[4], q4[4];
; #pragma unroll
;         for (int pt = 0; pt < 4; ++pt) { const size_t o = (size_t)(row0 + 16 * pt + fr) * QKW + h * DK + 16 * wave + 4 * fq; k4[pt] = ld_bf4(Kb + o); q4[pt] = lat ? ld_bf4(Qb + o) : (f32x4){0.f, 0.f, 0.f, 0.f}; }
.LBB0_1105:
	s_and_b32 s10, s12, 3
	s_add_i32 s45, s45, 35
	s_cmpk_lt_u32 s45, 0x47
	s_cselect_b64 s[42:43], -1, 0
	s_cmpk_gt_u32 s45, 0x46
	s_waitcnt lgkmcnt(0)
	s_barrier
	s_cselect_b64 s[68:69], -1, 0
	s_or_b64 s[48:49], s[46:47], s[42:43]
	s_mov_b64 s[98:99], s[48:49]
	s_andn2_b64 vcc, exec, s[48:49]
	s_cbranch_vccnz .LBB0_1107
	v_add_u32_e32 v0, s44, v25
	v_ashrrev_i32_e32 v1, 31, v0
	v_lshlrev_b64 v[0:1], 11, v[0:1]
	v_lshl_add_u64 v[0:1], s[50:51], 0, v[0:1]
	s_lshl_b32 s88, s10, 9
	v_lshl_add_u64 v[4:5], v[0:1], 0, s[88:89]
	v_lshl_add_u64 v[128:129], v[34:35], 1, v[4:5]
	v_lshl_add_u64 v[130:131], v[36:37], 1, v[4:5]
	v_lshl_add_u64 v[132:133], v[38:39], 1, v[4:5]
	v_lshl_add_u64 v[134:135], v[40:41], 1, v[4:5]
	global_load_dwordx4 v[136:139], v[128:129], off
	global_load_dwordx4 v[140:143], v[130:131], off
	global_load_dwordx4 v[144:147], v[132:133], off
	global_load_dwordx4 v[148:151], v[134:135], off
.LBB0_1107:
	v_readlane_b32 s16, v254, 17
	s_sext_i32_i16 s13, s13
	s_and_b64 s[48:49], s[42:43], exec
	v_readlane_b32 s17, v254, 18
	v_readlane_b32 s18, v254, 19
	v_readlane_b32 s19, v254, 20
	v_readlane_b32 s20, v254, 21
	v_readlane_b32 s21, v254, 22
	v_readlane_b32 s22, v254, 23
	v_readlane_b32 s23, v254, 24
	s_cselect_b32 s49, s17, s21
	s_cselect_b32 s48, s16, s20
	s_cselect_b32 s14, s19, s23
	s_cselect_b32 s15, s18, s22
	v_add_u32_e32 v0, s44, v24
	s_lshl_b32 s44, s13, 4
	s_ashr_i32 s45, s44, 31
	v_ashrrev_i32_e32 v1, 31, v0
	v_add_u32_e32 v6, 16, v0
	v_lshl_add_u64 v[2:3], s[44:45], 1, v[28:29]
	v_lshlrev_b64 v[58:59], 9, v[0:1]
	v_ashrrev_i32_e32 v7, 31, v6
	v_lshl_add_u64 v[4:5], v[2:3], 0, v[58:59]
	v_lshlrev_b64 v[56:57], 9, v[6:7]
	v_lshl_add_u64 v[6:7], v[2:3], 0, v[56:57]
	global_load_dwordx4 v[20:23], v[4:5], off
	global_load_dwordx4 v[16:19], v[6:7], off
	v_add_u32_e32 v4, 32, v0
	v_add_u32_e32 v0, 48, v0
	v_ashrrev_i32_e32 v5, 31, v4
	v_ashrrev_i32_e32 v1, 31, v0
	v_lshlrev_b64 v[10:11], 9, v[4:5]
	v_lshlrev_b64 v[8:9], 9, v[0:1]
	v_lshl_add_u64 v[4:5], v[2:3], 0, v[10:11]
	v_lshl_add_u64 v[0:1], v[2:3], 0, v[8:9]
	global_load_dwordx4 v[12:15], v[4:5], off
	s_nop 0
	global_load_dwordx4 v[0:3], v[0:1], off
	v_lshl_add_u64 v[4:5], s[48:49], 0, v[26:27]
	s_lshl_b32 s44, s10, 9
	s_mov_b32 s45, s89
	v_lshl_add_u64 v[4:5], v[4:5], 0, s[44:45]
	v_lshl_add_u64 v[4:5], v[4:5], 0, s[84:85]
	v_lshlrev_b32_e32 v6, 2, v24
	v_mov_b32_e32 v7, v27
	v_lshl_add_u64 v[4:5], v[4:5], 0, v[6:7]
	s_movk_i32 s45, 0x1000
	v_add_co_u32_e32 v6, vcc, s45, v4
	s_movk_i32 s45, 0x2000
	s_nop 0
	v_addc_co_u32_e32 v7, vcc, 0, v5, vcc
	v_add_co_u32_e32 v60, vcc, s45, v4
	s_lshl_b32 s88, s10, 7
	s_nop 0
	v_addc_co_u32_e32 v61, vcc, 0, v5, vcc
	s_movk_i32 s45, 0x3000
	global_load_dword v70, v[60:61], off offset:-4096
	global_load_dword v68, v[60:61], off
	global_load_dword v66, v[60:61], off offset:2048
	v_add_co_u32_e32 v60, vcc, s45, v4
	s_add_u32 s15, s15, s44
	s_nop 0
	v_addc_co_u32_e32 v61, vcc, 0, v5, vcc
	global_load_dword v73, v[4:5], off
	global_load_dword v72, v[4:5], off offset:2048
	global_load_dword v71, v[6:7], off offset:2048
	global_load_dword v69, v[60:61], off
	global_load_dword v67, v[60:61], off offset:2048
	s_addc_u32 s14, s14, 0
	v_lshl_add_u64 v[64:65], v[30:31], 0, s[88:89]
	s_add_u32 s44, s15, s84
	v_lshl_add_u64 v[58:59], v[58:59], 0, v[64:65]
	s_addc_u32 s45, s14, s85
	v_lshl_add_u64 v[60:61], v[58:59], 1, s[96:97]
	global_load_dwordx4 v[4:7], v95, s[44:45]
	global_load_dwordx2 v[62:63], v[60:61], off
	v_cndmask_b32_e64 v55, 0, 1, s[46:47]
	v_mov_b32_e32 v111, 0
	v_cmp_ne_u32_e64 s[44:45], 1, v55
	s_andn2_b64 vcc, exec, s[46:47]
	v_mov_b32_e32 v116, 0
	v_mov_b32_e32 v117, 0
	v_mov_b32_e32 v118, 0
	v_mov_b32_e32 v119, 0
	v_readlane_b32 s24, v254, 25
	v_readlane_b32 s25, v254, 26
	v_readlane_b32 s26, v254, 27
	v_readlane_b32 s27, v254, 28
	v_readlane_b32 s28, v254, 29
	v_readlane_b32 s29, v254, 30
	v_readlane_b32 s30, v254, 31
	v_readlane_b32 s31, v254, 32
	s_cbranch_vccnz .LBB0_1109
	v_lshl_add_u64 v[58:59], v[58:59], 1, s[0:1]
	global_load_dwordx2 v[152:153], v[58:59], off
; __device__ __forceinline__ float bf2f(unsigned short h) { return __uint_as_float((unsigned)h << 16); }
; __device__ __forceinline__ unsigned f2bfhw(float f) { return (unsigned)__builtin_bit_cast(unsigned short, (__bf16)f); }
; __device__ __forceinline__ f32x4 ld_bf4(const bf16_t* p) { u32x2 w = *(const u32x2*)p; return (f32x4){__uint_as_float(w.x << 16), __uint_as_float(w.x & 0xffff0000u), __uint_as_float(w.y << 16), __uint_as_float(w.y & 0xffff0000u)}; }
; __device__ __forceinline__ void gla_prep(LAS unsigned char* lds, int ufirst, int ucount, const bf16_t* Qb, const bf16_t* Kb, const bf16_t* Vb, const bf16_t* LR, ...
;     ...
;             for (int j = 0; j < 4; ++j) { const int idx = tid + 512 * j, sp = idx & 63, c8 = (idx >> 6) * 8; const bf16x8 v = *(const bf16x8*)(Vb + (size_t)(row0 + sp) * VW + h * DV + c8);
; #pragma unroll
;                 for (int e = 0; e < 8; ++e) vT[(c8 + e) * 72 + sp] = (bf16_t)v[e]; }
;         }
;         bf16x8 afr[4], bfr;
; #pragma unroll
;         for (int pt = 0; pt < 4; ++pt) afr[pt] = *(const bf16x8*)(LR + (size_t)(row0 + 16 * pt + fr) * 256 + dir * 16 + (fq & 1) * 8);
;         { const float* wp = wsrc + (size_t)((fq & 1) * 8) * QKW + h * DK + 16 * wave + fr;
; #pragma unroll
;           for (int e = 0; e < 8; ++e) { const float wv = wp[e * QKW]; const unsigned hi = f2bfhw(wv); const float res = wv - bf2f((unsigned short)hi); bfr[e] = (short)(fq < 2 ? hi : f2bfhw(res)); } }
;         const f32x4 bias4 = *(const f32x4*)(bsrc + h * DK + 16 * wave + 4 * fq);
;         f32x4 k4[4], q4[4];
; #pragma unroll
;         for (int pt = 0; pt < 4; ++pt) { const size_t o = (size_t)(row0 + 16 * pt + fr) * QKW + h * DK + 16 * wave + 4 * fq; k4[pt] = ld_bf4(Kb + o); q4[pt] = lat ? ld_bf4(Qb + o) : (f32x4){0.f, 0.f, 0.f, 0.f}; }
.LBB0_1109:
	v_lshl_add_u64 v[56:57], v[56:57], 0, v[64:65]
	v_lshl_add_u64 v[58:59], v[56:57], 1, s[96:97]
	global_load_dwordx2 v[60:61], v[58:59], off
	s_and_b64 vcc, exec, s[44:45]
	v_mov_b32_e32 v113, 0
	v_mov_b32_e32 v114, 0
	v_mov_b32_e32 v115, 0
	s_cbranch_vccnz .LBB0_1111
	v_lshl_add_u64 v[56:57], v[56:57], 1, s[0:1]
	global_load_dwordx2 v[154:155], v[56:57], off
.LBB0_1111:
	v_lshl_add_u64 v[10:11], v[10:11], 0, v[64:65]
	v_lshl_add_u64 v[56:57], v[10:11], 1, s[96:97]
	global_load_dwordx2 v[58:59], v[56:57], off
	v_mov_b32_e32 v55, 0
	s_and_b64 vcc, exec, s[44:45]
	v_mov_b32_e32 v108, 0
	v_mov_b32_e32 v109, 0
	v_mov_b32_e32 v110, 0
	v_mov_b32_e32 v112, 0
	s_cbranch_vccnz .LBB0_1113
	v_lshl_add_u64 v[10:11], v[10:11], 1, s[0:1]
	global_load_dwordx2 v[156:157], v[10:11], off
.LBB0_1113:
	v_lshl_add_u64 v[8:9], v[8:9], 0, v[64:65]
	v_lshl_add_u64 v[10:11], v[8:9], 1, s[96:97]
	global_load_dwordx2 v[56:57], v[10:11], off
	s_and_b64 vcc, exec, s[44:45]
	v_mov_b32_e32 v105, 0
	v_mov_b32_e32 v106, 0
	v_mov_b32_e32 v107, 0
	s_cbranch_vccnz .LBB0_1115
	v_lshl_add_u64 v[8:9], v[8:9], 1, s[0:1]
	global_load_dwordx2 v[158:159], v[8:9], off
.LBB0_1115:
	s_waitcnt vmcnt(0)
	s_andn2_b64 vcc, exec, s[98:99]
	s_cbranch_vccnz .Lgla_skipv
	ds_write_b16 v87, v136 offset:44032
	ds_write_b16_d16_hi v87, v136 offset:44176
	ds_write_b16 v87, v137 offset:44320
	ds_write_b16_d16_hi v87, v137 offset:44464
	ds_write_b16 v87, v138 offset:44608
	ds_write_b16_d16_hi v87, v138 offset:44752
	ds_write_b16 v87, v139 offset:44896
	ds_write_b16_d16_hi v88, v139 offset:44032
	ds_write_b16 v89, v140 offset:44032
	ds_write_b16_d16_hi v89, v140 offset:44176
	ds_write_b16 v89, v141 offset:44320
	ds_write_b16_d16_hi v89, v141 offset:44464
	ds_write_b16 v89, v142 offset:44608
	ds_write_b16_d16_hi v89, v142 offset:44752
	ds_write_b16 v89, v143 offset:44896
	ds_write_b16_d16_hi v90, v143 offset:44032
	ds_write_b16 v91, v144 offset:44032
	ds_write_b16_d16_hi v91, v144 offset:44176
	ds_write_b16 v91, v145 offset:44320
	ds_write_b16_d16_hi v91, v145 offset:44464
	ds_write_b16 v91, v146 offset:44608
	ds_write_b16_d16_hi v91, v146 offset:44752
	ds_write_b16 v91, v147 offset:44896
	ds_write_b16_d16_hi v92, v147 offset:44032
	ds_write_b16 v93, v148 offset:44032
	ds_write_b16_d16_hi v93, v148 offset:44176
	ds_write_b16 v93, v149 offset:44320
	ds_write_b16_d16_hi v93, v149 offset:44464
	ds_write_b16 v93, v150 offset:44608
	ds_write_b16_d16_hi v93, v150 offset:44752
	ds_write_b16 v93, v151 offset:44896
	ds_write_b16_d16_hi v94, v151 offset:44032
.Lgla_skipv:
	s_andn2_b64 vcc, exec, s[46:47]
	s_cbranch_vccnz .Lgla_skipq
	v_lshlrev_b32_e32 v116, 16, v152
	v_and_b32_e32 v117, 0xffff0000, v152
	v_lshlrev_b32_e32 v118, 16, v153
	v_and_b32_e32 v119, 0xffff0000, v153
	v_lshlrev_b32_e32 v111, 16, v154
	v_and_b32_e32 v113, 0xffff0000, v154
	v_lshlrev_b32_e32 v114, 16, v155
	v_and_b32_e32 v115, 0xffff0000, v155
	v_lshlrev_b32_e32 v108, 16, v156
	v_and_b32_e32 v109, 0xffff0000, v156
	v_lshlrev_b32_e32 v110, 16, v157
	v_and_b32_e32 v112, 0xffff0000, v157
	v_lshlrev_b32_e32 v55, 16, v158
	v_and_b32_e32 v105, 0xffff0000, v158
	v_lshlrev_b32_e32 v106, 16, v159
	v_and_b32_e32 v107, 0xffff0000, v159
